# dil band item prologue: conservative s_waitcnt vmcnt(0) between the Q loads and the K/V chunk-0 loads removed (both latencies overlap)
# speedup vs baseline: 1.0073x; 1.0073x over previous
; #define LAS __attribute__((address_space(3)))
; template <int HD, int DV, int HW, int MODE> ...
;     ...
;     const int w = __builtin_amdgcn_readfirstlane(tid >> 6), lane = tid & 63, ql = lane & 31, hh = lane >> 5;
;     const int iw = i0 + 32 * w, x32a = ((lane ^ 32) << 2);
;     LAS unsigned char* Kl = lds; LAS unsigned char* Vl = lds + KB;
;     bf16x8 qf[KS];
;     { const bf16_t* qrow = qp + (tok0 + (size_t)r * (iw + ql)) * ld + 8 * hh;
; #pragma unroll
;       for (int ks = 0; ks < KS; ++ks) qf[ks] = *(const bf16x8*)(qrow + 16 * ks); }
;     f32x16 O[NTV];
; #pragma unroll
;     for (int t = 0; t < NTV; ++t)
; #pragma unroll
;         for (int i = 0; i < 16; ++i) O[t][i] = 0.f;
;     float m = (MODE == 1) ? sink2 : -1e30f, l = (MODE == 1 && hh == 0) ? 1.0f : 0.f;
;     const int pi = (ql & ~12) | ((ql & 4) << 1) | ((ql & 8) >> 1);
;     const LAS unsigned char* kread = Kl + pi * RSK + 16 * hh;
;     const int g16 = lane >> 4, i16 = lane & 15;
;     const LAS unsigned char* vread = Vl + (8 * (g16 >> 1) + (i16 >> 2)) * RSV + (16 * (g16 & 1) + 4 * (i16 & 3)) * 2;
;     u32x4 kreg[KLD], vreg[VLD];
;     auto prefetch = [&](int c) {
;         const int jc = i0 - HW + CR * c;
; #pragma unroll
;         for (int i = 0; i < KLD; ++i) { const int idx = tid + 512 * i, row = idx / KCH, ch = idx % KCH, j = jc + row;
;             kreg[i] = (j >= 0 && j < L) ? *(const u32x4*)(kp + (tok0 + (size_t)r * j) * ld + ch * 8) : (u32x4){0, 0, 0, 0}; }
; #pragma unroll
;         for (int i = 0; i < VLD; ++i) { const int idx = tid + 512 * i, row = idx / VCH, ch = idx % VCH, j = jc + row;
;             vreg[i] = (j >= 0 && j < L) ? *(const u32x4*)(vp + (tok0 + (size_t)r * j) * ld + ch * 8) : (u32x4){0, 0, 0, 0}; }
;     };
;     prefetch(0);
; __device__ __forceinline__ void dil_attn_phase(const Params& p, int half, LAS unsigned char* lds) {
;     ...
;         const int g = it >> 9, rem = it & 511, bl = rem >> 8, rest = rem & 255, h = rest & 7, cr = rest >> 3;
;         const int r = g == 0 ? 1 : (g == 1 ? 4 : 16), L = SEQ / r, pr = cr % r, qc = cr / r;
;         const size_t tok0 = (size_t)bl * SEQ + pr;
;         band_item<128, 128, 64, 0>(PROJ + g * 1024 + h * 128, PROJ + 3072 + g * 1024 + h * 128, PROJ + 6144 + h * 128, 8192, tok0, r, L, qc * 256, 0.f,
.LBB0_84:
	s_ashr_i32 s26, s15, 9
	s_and_b32 s21, s15, 7
	s_lshr_b32 s2, s15, 3
	s_bfe_u32 s4, s15, 0x50003
	s_cmp_eq_u32 s26, 1
	s_cselect_b32 s5, 2, 4
	s_cselect_b32 s10, 3, 15
	s_cmpk_lt_u32 s15, 0x200
	s_cselect_b32 s25, 0, s5
	s_cselect_b32 s5, 0, s10
	s_lshr_b32 s22, s4, s25
	s_lshl_b32 s4, s15, 5
	s_and_b32 s2, s5, s2
	s_and_b32 s4, s4, 0x2000
	s_or_b32 s96, s2, s4
	s_lshl_b32 s4, s26, 10
	s_ashr_i32 s5, s4, 31
	s_lshr_b32 s27, 0x2000, s25
	s_lshl_b64 s[4:5], s[4:5], 1
	s_add_u32 s2, s84, s4
	s_addc_u32 s11, s85, s5
	s_lshl_b32 s23, s21, 8
	s_add_u32 s10, s2, s23
	s_addc_u32 s11, s11, 0
	s_add_u32 s2, s87, s4
	s_addc_u32 s4, s86, s5
	v_mov_b32_e32 v23, v207
	s_add_u32 s46, s2, s23
	s_addc_u32 s47, s4, 0
	v_readfirstlane_b32 s2, v23
	s_ashr_i32 s29, s2, 1
	s_lshl_b32 s34, s22, 8
	s_andn2_b32 s29, s29, 31
	v_and_b32_e32 v22, 31, v23
	s_add_i32 s28, s29, s34
	s_waitcnt lgkmcnt(0)
	v_or_b32_e32 v2, s28, v22
	v_ashrrev_i32_e32 v3, 31, v2
	v_lshlrev_b64 v[2:3], s25, v[2:3]
	v_lshl_add_u64 v[160:161], v[2:3], 0, s[96:97]
	v_bfe_u32 v163, v23, 5, 1
	v_lshlrev_b64 v[2:3], 14, v[160:161]
	v_lshl_add_u64 v[2:3], s[10:11], 0, v[2:3]
	v_lshlrev_b32_e32 v16, 4, v163
	v_mov_b32_e32 v17, v0
	v_lshl_add_u64 v[2:3], v[2:3], 0, v[16:17]
	global_load_dwordx4 v[96:99], v[2:3], off
	global_load_dwordx4 v[100:103], v[2:3], off offset:32
	global_load_dwordx4 v[104:107], v[2:3], off offset:64
	global_load_dwordx4 v[108:111], v[2:3], off offset:96
	global_load_dwordx4 v[112:115], v[2:3], off offset:128
	global_load_dwordx4 v[116:119], v[2:3], off offset:160
	global_load_dwordx4 v[120:123], v[2:3], off offset:192
	global_load_dwordx4 v[124:127], v[2:3], off offset:224
	v_ashrrev_i32_e32 v1, 31, v23
	v_lshrrev_b32_e32 v1, 28, v1
	v_add_u32_e32 v1, v23, v1
	v_ashrrev_i32_e32 v17, 4, v1
	v_and_b32_e32 v1, -16, v1
	s_sub_i32 s4, s34, 64
	v_sub_u32_e32 v24, v23, v1
	v_mov_b32_e32 v2, v0
	v_mov_b32_e32 v3, v0
	v_add_u32_e32 v12, s4, v17
	v_mov_b32_e32 v1, v0
	v_lshlrev_b32_e32 v4, 3, v24
	v_mov_b64_e32 v[130:131], v[2:3]
	v_cmp_gt_u32_e32 vcc, s27, v12
	v_ashrrev_i32_e32 v5, 31, v4
	v_mov_b64_e32 v[128:129], v[0:1]
	s_and_saveexec_b64 s[40:41], vcc
	s_cbranch_execz .LBB0_86
	v_mov_b32_e32 v13, v0
	v_lshlrev_b64 v[6:7], s25, v[12:13]
	v_lshl_add_u64 v[6:7], v[6:7], 0, s[96:97]
	v_lshlrev_b64 v[6:7], 14, v[6:7]
	v_lshl_add_u64 v[6:7], s[46:47], 0, v[6:7]
	v_lshl_add_u64 v[6:7], v[4:5], 1, v[6:7]
	global_load_dwordx4 v[128:131], v[6:7], off
